# stack of small latency removals: selection LDS-DMA ring, W/H3 three-deep loads, P6 gemm2 early loads, transpose_reduce64 lane ops, sample conv row loads batched
# speedup vs baseline: 1.0007x; 1.0007x over previous
; __device__ __forceinline__ float bf2f(u16 h) { return __uint_as_float(((unsigned)h) << 16); }
; __device__ __forceinline__ float wsum(float v) { v = dpp_row_sum16(v); v += __shfl_xor(v, 16); v += __shfl_xor(v, 32); return v; }
; __device__ __forceinline__ float siluf_(float x) { return x * __builtin_amdgcn_rcpf(1.f + __expf(-x)); }
; __device__ __forceinline__ void gdn_sample_item(const Params& p, int item, char* smem) {
;     ...
;   float cval[4];
;   {
;     const int type = tid >> 7, c = tid & 127;
;     const int col = type * 512 + h * 128 + c;
;     const float w0 = p.conv_w[col], w1 = p.conv_w[1536 + col], w2 = p.conv_w[3072 + col], w3 = p.conv_w[4608 + col];
;     const float* sc = p.state_conv + (size_t)bs * 3 * 1536 + col;
;     float x0 = sc[0], x1 = sc[1536], x2 = sc[3072];
; #pragma unroll
;     for (int t = 0; t < 4; t++) {
;       float x3 = bf2f(RAW[(size_t)(tokb + t) * 1536 + col]);
;       float c4 = x0 * w0 + x1 * w1 + x2 * w2 + x3 * w3;
;       cval[t] = siluf_(c4);
;       x0 = x1; x1 = x2; x2 = x3;
;       float s = wsum(cval[t] * cval[t]);
;       if (lane == 0) red[t * 4 + w] = s;
;     }
;   }
.LBB0_916:
	s_add_i32 s0, s17, 0x800
	s_cmpk_lt_i32 s0, 0x800
	s_cbranch_scc1 .LBB0_915
	s_and_b32 s26, s0, 3
	s_lshl_b32 s28, s26, 7
	v_or_b32_e32 v12, s28, v20
	v_readlane_b32 s56, v254, 3
	v_lshlrev_b32_e32 v0, 2, v12
	v_readlane_b32 s60, v254, 7
	v_readlane_b32 s61, v254, 8
	s_lshr_b32 s1, s17, 2
	s_and_b32 s29, s0, 0x1fc
	v_lshl_add_u64 v[2:3], s[60:61], 0, v[0:1]
	v_add_co_u32_e32 v14, vcc, 0x1000, v2
	s_mul_i32 s2, s1, 0x1200
	s_nop 0
	v_addc_co_u32_e32 v15, vcc, 0, v3, vcc
	s_or_b32 s27, s29, 0x4000
	v_add_co_u32_e32 v16, vcc, 0x3000, v2
	s_lshl_b64 s[0:1], s[2:3], 2
	s_nop 0
	v_addc_co_u32_e32 v17, vcc, 0, v3, vcc
	s_add_u32 s0, s48, s0
	v_add_co_u32_e32 v18, vcc, s18, v2
	s_addc_u32 s1, s49, s1
	s_nop 0
	v_addc_co_u32_e32 v19, vcc, 0, v3, vcc
	v_lshl_add_u64 v[2:3], s[0:1], 0, v[0:1]
	s_barrier
	global_load_dword v13, v[14:15], off offset:2048
	v_add_co_u32_e32 v66, vcc, s19, v2
	global_load_dword v14, v0, s[60:61]
	global_load_dword v11, v0, s[0:1]
	v_addc_co_u32_e32 v67, vcc, 0, v3, vcc
	s_mul_i32 s30, s27, 0x600
	v_add_co_u32_e32 v68, vcc, s20, v2
	v_add_lshl_u32 v0, v12, s30, 1
	s_nop 0
	v_addc_co_u32_e32 v69, vcc, 0, v3, vcc
	global_load_ushort v2, v0, s[78:79]
	global_load_dword v3, v[66:67], off offset:2048
	s_nop 0
	global_load_dword v0, v[68:69], off
	s_nop 0
	global_load_dword v16, v[16:17], off
	s_nop 0
	global_load_dword v15, v[18:19], off offset:2048
	s_add_i32 s31, s30, 0x600
	v_add_lshl_u32 v18, v12, s31, 1
	global_load_ushort a196, v18, s[78:79]
	s_add_i32 s34, s31, 0x600
	v_add_lshl_u32 v19, v12, s34, 1
	global_load_ushort a197, v19, s[78:79]
	s_or_b32 s98, s17, 0x4003
	s_mul_i32 s98, s98, 0x600
	v_add_lshl_u32 v18, v12, s98, 1
	global_load_ushort a198, v18, s[78:79]
	v_cmp_lt_i32_e32 vcc, v27, v28
	v_readlane_b32 s57, v254, 4
	v_readlane_b32 s58, v254, 5
	v_cndmask_b32_e32 v18, v5, v27, vcc
	v_lshlrev_b32_e32 v65, 2, v18
	v_cmp_lt_i32_e32 vcc, v29, v28
	v_readlane_b32 s59, v254, 6
	v_readlane_b32 s62, v254, 9
	v_cndmask_b32_e32 v19, v5, v29, vcc
	v_lshlrev_b32_e32 v66, 2, v19
	v_readlane_b32 s63, v254, 10
	v_readlane_b32 s64, v254, 11
	v_readlane_b32 s65, v254, 12
	v_readlane_b32 s66, v254, 13
	v_readlane_b32 s67, v254, 14
	v_readlane_b32 s68, v254, 15
	v_readlane_b32 s69, v254, 16
	v_readlane_b32 s70, v254, 17
	v_readlane_b32 s71, v254, 18
	s_waitcnt vmcnt(4)
	v_lshlrev_b32_e32 v17, 16, v2
	s_waitcnt vmcnt(3)
	v_mul_f32_e32 v2, v13, v3
	v_fmac_f32_e32 v2, v14, v11
	s_waitcnt vmcnt(1)
	v_fmac_f32_e32 v2, v16, v0
	s_waitcnt vmcnt(0)
	v_fmac_f32_e32 v2, v15, v17
	v_mul_f32_e32 v11, 0xbfb8aa3b, v2
	v_exp_f32_e32 v11, v11
	s_nop 0
	v_add_f32_e32 v11, 1.0, v11
	v_rcp_f32_e32 v11, v11
	s_nop 0
	v_mul_f32_e32 v2, v2, v11
	v_mul_f32_e32 v11, v2, v2
	s_nop 1
	v_mov_b32_dpp v11, v11 quad_perm:[1,0,3,2] row_mask:0xf bank_mask:0xf bound_ctrl:1
	v_fmac_f32_e32 v11, v2, v2
	s_nop 1
	v_add_f32_dpp v11, v11, v11 quad_perm:[2,3,0,1] row_mask:0xf bank_mask:0xf bound_ctrl:1
	s_nop 1
	v_add_f32_dpp v11, v11, v11 row_half_mirror row_mask:0xf bank_mask:0xf bound_ctrl:1
	s_nop 1
	v_add_f32_dpp v11, v11, v11 row_mirror row_mask:0xf bank_mask:0xf bound_ctrl:1
	ds_bpermute_b32 v18, v65, v11
	s_waitcnt lgkmcnt(0)
	v_add_f32_e32 v11, v11, v18
	ds_bpermute_b32 v18, v66, v11
	s_and_saveexec_b64 s[14:15], s[4:5]
	s_cbranch_execz .LBB0_919
	s_waitcnt lgkmcnt(0)
	v_add_f32_e32 v11, v11, v18
	ds_write_b32 v21, v11 offset:7168
.LBB0_919:
	s_or_b64 exec, exec, s[14:15]
	s_add_i32 s31, s30, 0x600
	v_add_lshl_u32 v11, v12, s31, 1
	v_accvgpr_read_b32 v11, a196
	v_mul_f32_e32 v19, v13, v0
	v_fmac_f32_e32 v19, v14, v3
	v_fmac_f32_e32 v19, v16, v17
	s_waitcnt lgkmcnt(0)
	v_lshlrev_b32_e32 v18, 16, v11
	v_fmac_f32_e32 v19, v15, v18
	v_mul_f32_e32 v3, 0xbfb8aa3b, v19
	v_exp_f32_e32 v3, v3
	s_nop 0
	v_add_f32_e32 v3, 1.0, v3
	v_rcp_f32_e32 v3, v3
	s_nop 0
	v_mul_f32_e32 v3, v19, v3
	v_mul_f32_e32 v11, v3, v3
	s_nop 1
	v_mov_b32_dpp v11, v11 quad_perm:[1,0,3,2] row_mask:0xf bank_mask:0xf bound_ctrl:1
	v_fmac_f32_e32 v11, v3, v3
	s_nop 1
	v_add_f32_dpp v11, v11, v11 quad_perm:[2,3,0,1] row_mask:0xf bank_mask:0xf bound_ctrl:1
	s_nop 1
	v_add_f32_dpp v11, v11, v11 row_half_mirror row_mask:0xf bank_mask:0xf bound_ctrl:1
	s_nop 1
	v_add_f32_dpp v11, v11, v11 row_mirror row_mask:0xf bank_mask:0xf bound_ctrl:1
	ds_bpermute_b32 v19, v65, v11
	s_waitcnt lgkmcnt(0)
	v_add_f32_e32 v11, v11, v19
	ds_bpermute_b32 v19, v66, v11
	s_and_saveexec_b64 s[14:15], s[4:5]
	s_cbranch_execz .LBB0_921
	s_waitcnt lgkmcnt(0)
	v_add_f32_e32 v11, v11, v19
	ds_write_b32 v21, v11 offset:7184
.LBB0_921:
	s_or_b64 exec, exec, s[14:15]
	s_add_i32 s34, s31, 0x600
	v_add_lshl_u32 v11, v12, s34, 1
	v_accvgpr_read_b32 v11, a197
	v_mul_f32_e32 v67, v13, v17
	v_fmac_f32_e32 v67, v14, v0
	v_fmac_f32_e32 v67, v16, v18
	s_waitcnt lgkmcnt(0)
	v_lshlrev_b32_e32 v19, 16, v11
	v_fmac_f32_e32 v67, v15, v19
	v_mul_f32_e32 v0, 0xbfb8aa3b, v67
	v_exp_f32_e32 v0, v0
	s_nop 0
	v_add_f32_e32 v0, 1.0, v0
	v_rcp_f32_e32 v0, v0
	s_nop 0
	v_mul_f32_e32 v11, v67, v0
	v_mul_f32_e32 v0, v11, v11
	s_nop 1
	v_mov_b32_dpp v0, v0 quad_perm:[1,0,3,2] row_mask:0xf bank_mask:0xf bound_ctrl:1
	v_fmac_f32_e32 v0, v11, v11
	s_nop 1
	v_add_f32_dpp v0, v0, v0 quad_perm:[2,3,0,1] row_mask:0xf bank_mask:0xf bound_ctrl:1
	s_nop 1
	v_add_f32_dpp v0, v0, v0 row_half_mirror row_mask:0xf bank_mask:0xf bound_ctrl:1
	s_nop 1
	v_add_f32_dpp v0, v0, v0 row_mirror row_mask:0xf bank_mask:0xf bound_ctrl:1
	ds_bpermute_b32 v67, v65, v0
	s_waitcnt lgkmcnt(0)
	v_add_f32_e32 v0, v0, v67
	ds_bpermute_b32 v67, v66, v0
	s_and_saveexec_b64 s[14:15], s[4:5]
	s_cbranch_execz .LBB0_923
	s_waitcnt lgkmcnt(0)
	v_add_f32_e32 v0, v0, v67
	ds_write_b32 v21, v0 offset:7200
.LBB0_923:
	s_or_b64 exec, exec, s[14:15]
	s_or_b32 s2, s17, 0x4003
	s_mul_i32 s35, s2, 0x600
	v_add_u32_e32 v0, s35, v12
	v_lshl_add_u64 v[68:69], v[0:1], 1, s[78:79]
	v_accvgpr_read_b32 v0, a198
	v_mul_f32_e32 v12, v13, v18
	v_fmac_f32_e32 v12, v14, v17
	v_fmac_f32_e32 v12, v16, v19
	v_lshlrev_b32_e32 v0, 16, v0
	v_fmac_f32_e32 v12, v15, v0
	v_mul_f32_e32 v0, 0xbfb8aa3b, v12
	v_exp_f32_e32 v0, v0
	s_nop 0
	v_add_f32_e32 v0, 1.0, v0
	v_rcp_f32_e32 v0, v0
	s_nop 0
	v_mul_f32_e32 v12, v12, v0
	v_mul_f32_e32 v0, v12, v12
	s_nop 1
	v_mov_b32_dpp v0, v0 quad_perm:[1,0,3,2] row_mask:0xf bank_mask:0xf bound_ctrl:1
	v_fmac_f32_e32 v0, v12, v12
	s_nop 1
	v_add_f32_dpp v0, v0, v0 quad_perm:[2,3,0,1] row_mask:0xf bank_mask:0xf bound_ctrl:1
	s_nop 1
	v_add_f32_dpp v0, v0, v0 row_half_mirror row_mask:0xf bank_mask:0xf bound_ctrl:1
	s_nop 1
	v_add_f32_dpp v0, v0, v0 row_mirror row_mask:0xf bank_mask:0xf bound_ctrl:1
	ds_bpermute_b32 v13, v65, v0
	s_waitcnt lgkmcnt(0)
	v_add_f32_e32 v0, v0, v13
	ds_bpermute_b32 v13, v66, v0
	s_and_saveexec_b64 s[14:15], s[4:5]
	s_cbranch_execnz .LBB0_938
	s_or_b64 exec, exec, s[14:15]
	s_and_saveexec_b64 s[14:15], s[8:9]
	s_cbranch_execnz .LBB0_939

; __device__ __forceinline__ void phase5(const Params& p, char* smem, const bool store_x = true) {
;     ...
;   uint4 pf_ts, pf_ti, pf_ha, pf_hb; float pf_ss = 1.f;
;   const u16* X1B = (const u16*)(ws + OFF_X1B);
;   const float* SSQ1 = (const float*)(ws + OFF_SSQ1);
;   float2v gf[8];
; #pragma unroll
;   for (int i = 0; i < 4; i++) { const float4 g4 = *(const float4*)(p.g_ffn + lane * 16 + i * 4); gf[2 * i] = float2v{g4.x, g4.y}; gf[2 * i + 1] = float2v{g4.z, g4.w}; }
;   {
;     const int tok0 = (int)blockIdx.x * 4 + w;
;     if (tok0 < NT) {
;       pf_ts = ((const uint4*)(TOPS + (size_t)tok0 * 256))[lane];
;       pf_ti = ((const uint4*)(TOPI + (size_t)tok0 * 256))[lane];
;       pf_ha = *(const uint4*)(X1B + (size_t)tok0 * 1024 + lane * 16);
;       pf_hb = *(const uint4*)(X1B + (size_t)tok0 * 1024 + lane * 16 + 8);
;       pf_ss = SSQ1[tok0];
;     }
;   }
.LBB0_1479:
	s_or_b64 exec, exec, s[0:1]
	v_readlane_b32 s0, v254, 48
	v_readlane_b32 s1, v254, 49
	s_and_b64 vcc, exec, s[0:1]
	s_cbranch_vccnz .Lp5a_done
	v_accvgpr_read_b32 v0, a129
	v_lshlrev_b32_e32 v6, 2, v18
	v_mov_b32_e32 v7, 0
	v_lshlrev_b32_e32 v176, 12, v0
	v_lshl_add_u64 v[0:1], s[78:79], 0, v[6:7]
	v_accvgpr_write_b32 a71, v1
	v_mov_b32_e32 v19, v7
	v_accvgpr_write_b32 a70, v0
	v_lshl_add_u64 v[0:1], s[48:49], 0, v[18:19]
	v_accvgpr_write_b32 a73, v1
	v_accvgpr_write_b32 a72, v0
	v_lshl_add_u64 v[0:1], s[54:55], 0, v[18:19]
	v_accvgpr_write_b32 a75, v1
	v_accvgpr_write_b32 a74, v0
	v_lshlrev_b32_e32 v0, 1, v18
	v_mov_b32_e32 v1, v7
	v_lshl_add_u64 v[188:189], s[2:3], 0, v[0:1]
	v_lshrrev_b32_e32 v0, 3, v182
	v_lshl_or_b32 v179, v0, 7, v176
	v_mul_i32_i24_e32 v3, 0xffffff84, v0
	v_lshlrev_b32_e32 v239, 4, v0
	v_and_b32_e32 v0, 32, v237
	v_cmp_eq_u32_e64 s[6:7], 0, v0
	v_mbcnt_lo_u32_b32 v0, -1, 0
	v_mbcnt_hi_u32_b32 v0, -1, v0
	v_and_b32_e32 v5, 64, v0
	v_xor_b32_e32 v4, 32, v0
	v_add_u32_e32 v5, 64, v5
	v_cmp_lt_i32_e32 vcc, v4, v5
	v_and_b32_e32 v1, 7, v237
	v_or_b32_e32 v177, v176, v18
	v_cndmask_b32_e32 v4, v0, v4, vcc
	v_lshlrev_b32_e32 v241, 2, v4
	v_and_b32_e32 v4, 16, v237
	v_cmp_eq_u32_e64 s[8:9], 0, v4
	v_xor_b32_e32 v4, 16, v0
	v_cmp_lt_i32_e32 vcc, v4, v5
	v_mul_i32_i24_e32 v2, -12, v182
	v_lshl_add_u64 v[190:191], s[80:81], 0, v[18:19]
	v_cndmask_b32_e32 v4, v0, v4, vcc
	v_lshlrev_b32_e32 v242, 2, v4
	v_and_b32_e32 v4, 8, v237
	v_cmp_eq_u32_e64 s[10:11], 0, v4
	v_xor_b32_e32 v4, 8, v0
	v_cmp_lt_i32_e32 vcc, v4, v5
	s_mov_b64 s[0:1], 0xaf35000
	v_readlane_b32 s56, v254, 19
	v_cndmask_b32_e32 v4, v0, v4, vcc
	v_lshlrev_b32_e32 v243, 2, v4
	v_and_b32_e32 v4, 4, v237
	v_cmp_eq_u32_e64 s[12:13], 0, v4
	v_xor_b32_e32 v4, 4, v0
	v_cmp_lt_i32_e32 vcc, v4, v5
	v_lshl_add_u64 v[192:193], v[190:191], 0, s[0:1]
	s_mov_b64 s[0:1], 0xbf35000
	v_cndmask_b32_e32 v0, v0, v4, vcc
	v_lshlrev_b32_e32 v244, 2, v0
	v_and_b32_e32 v0, 3, v237
	v_cmp_eq_u32_e64 s[14:15], 0, v0
	v_mad_u32_u24 v0, v1, 7, 1
	v_accvgpr_write_b32 a68, v0
	v_readlane_b32 s70, v254, 33
	v_readlane_b32 s71, v254, 34
	v_add_u32_e32 v0, v177, v2
	v_mul_u32_u24_e32 v238, 7, v1
	v_cmp_gt_u32_e64 s[4:5], 8, v182
	v_lshl_add_u64 v[194:195], v[190:191], 0, s[0:1]
	v_cmp_eq_u32_e64 s[16:17], 7, v1
	v_mad_u32_u24 v251, v1, 7, 2
	v_mad_u32_u24 v181, v1, 7, 3
	v_mad_u32_u24 v184, v1, 7, 4
	v_mad_u32_u24 v245, v1, 7, 5
	v_mad_u32_u24 v250, v1, 7, 6
	v_accvgpr_write_b32 a69, v7
	v_lshl_add_u64 v[196:197], s[70:71], 0, v[6:7]
	v_and_b32_e32 v180, 60, v182
	v_accvgpr_write_b32 a76, v0
	s_movk_i32 s33, 0xffc0
	v_mov_b32_e32 v252, 0xff61b1e6
	s_mov_b32 s38, 0x3fb8aa3b
	v_add_u32_e32 v253, v179, v3
	v_mov_b32_e32 v178, 1
	v_mov_b32_e32 v105, 0x358637bd
	s_mov_b32 s39, 0x800000
	s_mov_b32 s40, 0x3f200000
	s_mov_b32 s41, 0xc2ce8ed0
	s_mov_b32 s42, 0x42b17218
	v_mov_b32_e32 v185, 0x3ca908c9
	s_brev_b32 s43, -2
	v_mov_b32_e32 v186, 0x7f800000
	s_mov_b32 s44, s96
	s_waitcnt vmcnt(0)
	v_mov_b32_e32 v240, v104
	v_readlane_b32 s57, v254, 20
	v_readlane_b32 s58, v254, 21
	v_readlane_b32 s59, v254, 22
	v_readlane_b32 s60, v254, 23
	v_readlane_b32 s61, v254, 24
	v_readlane_b32 s62, v254, 25
	v_readlane_b32 s63, v254, 26
	v_readlane_b32 s64, v254, 27
	v_readlane_b32 s65, v254, 28
	v_readlane_b32 s66, v254, 29
	v_readlane_b32 s67, v254, 30
	v_readlane_b32 s68, v254, 31
	v_readlane_b32 s69, v254, 32
	v_accvgpr_read_b32 v0, a129
	s_nop 0
	v_readfirstlane_b32 s56, v0
	s_lshl_b32 s56, s56, 13
	s_add_u32 s56, s56, 0x8000
	s_mov_b32 s57, 0
	s_mov_b32 s58, s96
	s_min_i32 s58, s58, 0x107f
	v_accvgpr_read_b32 v0, a129
	v_lshl_add_u32 v0, s58, 2, v0
	v_lshlrev_b32_e32 v2, 10, v0
	v_accvgpr_read_b32 v4, a72
	v_accvgpr_read_b32 v5, a73
	v_add_co_u32_e32 v4, vcc, v4, v2
	s_nop 1
	v_addc_co_u32_e32 v5, vcc, 0, v5, vcc
	v_accvgpr_read_b32 v6, a74
	v_accvgpr_read_b32 v7, a75
	v_add_co_u32_e32 v6, vcc, v6, v2
	s_nop 1
	v_addc_co_u32_e32 v7, vcc, 0, v7, vcc
	s_mov_b32 s59, 0
	s_lshl_b32 s59, s59, 11
	s_add_u32 s59, s59, s56
	s_mov_b32 m0, s59
	s_nop 0
	global_load_lds_dwordx4 v[4:5], off
	s_add_u32 s59, s59, 0x400
	s_mov_b32 m0, s59
	s_nop 0
	global_load_lds_dwordx4 v[6:7], off
	s_mul_i32 s58, s82, 1
	s_add_i32 s58, s58, s96
	s_min_i32 s58, s58, 0x107f
	v_accvgpr_read_b32 v0, a129
	v_lshl_add_u32 v0, s58, 2, v0
	v_lshlrev_b32_e32 v2, 10, v0
	v_accvgpr_read_b32 v4, a72
	v_accvgpr_read_b32 v5, a73
	v_add_co_u32_e32 v4, vcc, v4, v2
	s_nop 1
	v_addc_co_u32_e32 v5, vcc, 0, v5, vcc
	v_accvgpr_read_b32 v6, a74
	v_accvgpr_read_b32 v7, a75
	v_add_co_u32_e32 v6, vcc, v6, v2
	s_nop 1
	v_addc_co_u32_e32 v7, vcc, 0, v7, vcc
	s_mov_b32 s59, 1
	s_lshl_b32 s59, s59, 11
	s_add_u32 s59, s59, s56
	s_mov_b32 m0, s59
	s_nop 0
	global_load_lds_dwordx4 v[4:5], off
	s_add_u32 s59, s59, 0x400
	s_mov_b32 m0, s59
	s_nop 0
	global_load_lds_dwordx4 v[6:7], off
	s_mul_i32 s58, s82, 2
	s_add_i32 s58, s58, s96
	s_min_i32 s58, s58, 0x107f
	v_accvgpr_read_b32 v0, a129
	v_lshl_add_u32 v0, s58, 2, v0
	v_lshlrev_b32_e32 v2, 10, v0
	v_accvgpr_read_b32 v4, a72
	v_accvgpr_read_b32 v5, a73
	v_add_co_u32_e32 v4, vcc, v4, v2
	s_nop 1
	v_addc_co_u32_e32 v5, vcc, 0, v5, vcc
	v_accvgpr_read_b32 v6, a74
	v_accvgpr_read_b32 v7, a75
	v_add_co_u32_e32 v6, vcc, v6, v2
	s_nop 1
	v_addc_co_u32_e32 v7, vcc, 0, v7, vcc
	s_mov_b32 s59, 2
	s_lshl_b32 s59, s59, 11
	s_add_u32 s59, s59, s56
	s_mov_b32 m0, s59
	s_nop 0
	global_load_lds_dwordx4 v[4:5], off
	s_add_u32 s59, s59, 0x400
	s_mov_b32 m0, s59
	s_nop 0
	global_load_lds_dwordx4 v[6:7], off
	s_waitcnt vmcnt(0)
	s_branch .LBB0_1482
; __device__ __forceinline__ void phase5(const Params& p, char* smem, const bool store_x = true) {
;     ...
;   for (int it = blockIdx.x; it < NT / 4; it += gridDim.x) {
;     const int tok = it * 4 + w;
;     float* xr = X + (size_t)tok * 1024 + lane * 16;
;     const float4 xv0 = *(const float4*)(xr), xv1 = *(const float4*)(xr + 4), xv2 = *(const float4*)(xr + 8), xv3 = *(const float4*)(xr + 12);
;     ((uint4*)tsL)[lane] = pf_ts;
;     ((uint4*)tiL)[lane] = pf_ti;
;     const uint4 cur_ha = pf_ha, cur_hb = pf_hb; const float cur_rs = rsqrtf(pf_ss * (1.f / 1024.f) + EPSF);
;     {
;       const int itn = it + (int)gridDim.x;
;       if (itn < NT / 4) {
;         const int tokn = itn * 4 + w;
;         pf_ts = ((const uint4*)(TOPS + (size_t)tokn * 256))[lane];
;         pf_ti = ((const uint4*)(TOPI + (size_t)tokn * 256))[lane];
;         pf_ha = *(const uint4*)(X1B + (size_t)tokn * 1024 + lane * 16);
;         pf_hb = *(const uint4*)(X1B + (size_t)tokn * 1024 + lane * 16 + 8);
;         pf_ss = SSQ1[tokn];
;       }
;     }
;     {
;       const int hd = lane >> 3, g = lane & 7;
;       const float* ts = tsL + hd * 32;
;       const int* ti = tiL + hd * 32;
;       float key[7]; int ij[7];
; #pragma unroll
;       for (int sl = 0; sl < 7; sl++) {
;         const int cid = g * 7 + sl;
;         const int t = ctab[cid];
;         ij[sl] = t;
;         float sum = ts[t >> 4] + ts[16 + (t & 15)];
;         unsigned k = (__float_as_uint(sum) & ~63u) | (unsigned)cid;
;         key[sl] = cid < 50 ? __uint_as_float(k) : NINF;
;       }
.LBB0_1482:
	s_waitcnt vmcnt(13)
	s_and_b32 s58, s57, 3
	s_lshl_b32 s58, s58, 11
	s_add_u32 s58, s58, s56
	s_sub_u32 s58, s58, 0x800
	v_sub_u32_e32 v31, v179, v176
	v_add_u32_e32 v31, s58, v31
	v_accvgpr_read_b32 v0, a129
	v_lshl_add_u32 v32, s44, 2, v0
	v_ashrrev_i32_e32 v33, 31, v32
	v_accvgpr_read_b32 v2, a70
	v_lshlrev_b64 v[0:1], 12, v[32:33]
	v_accvgpr_read_b32 v3, a71
	v_lshl_add_u64 v[198:199], v[2:3], 0, v[0:1]
	s_add_i32 s44, s44, s82
	s_cmpk_gt_i32 s44, 0x107f
	s_cselect_b64 s[34:35], -1, 0
	v_accvgpr_write_b32 a12, v96
	v_accvgpr_write_b32 a14, v98
	v_accvgpr_write_b32 a8, v100
	v_accvgpr_write_b32 a10, v102
	s_and_b64 vcc, exec, s[34:35]
	v_accvgpr_write_b32 a13, v97
	v_accvgpr_write_b32 a15, v99
	v_accvgpr_write_b32 a9, v101
	v_accvgpr_write_b32 a11, v103
	s_lshl_b32 s58, s82, 1
	s_add_i32 s58, s58, s44
	s_min_i32 s58, s58, 0x107f
	v_accvgpr_read_b32 v0, a129
	v_lshl_add_u32 v0, s58, 2, v0
	v_lshlrev_b32_e32 v2, 10, v0
	v_accvgpr_read_b32 v4, a72
	v_accvgpr_read_b32 v5, a73
	v_add_co_u32_e32 v4, vcc, v4, v2
	s_nop 1
	v_addc_co_u32_e32 v5, vcc, 0, v5, vcc
	v_accvgpr_read_b32 v6, a74
	v_accvgpr_read_b32 v7, a75
	v_add_co_u32_e32 v6, vcc, v6, v2
	s_nop 1
	v_addc_co_u32_e32 v7, vcc, 0, v7, vcc
	s_add_u32 s59, s57, 3
	s_and_b32 s59, s59, 3
	s_lshl_b32 s59, s59, 11
	s_add_u32 s59, s59, s56
	s_mov_b32 m0, s59
	s_nop 0
	global_load_lds_dwordx4 v[4:5], off
	s_add_u32 s59, s59, 0x400
	s_mov_b32 m0, s59
	s_nop 0
	global_load_lds_dwordx4 v[6:7], off
	s_add_u32 s57, s57, 1
.LBB0_1484:
	ds_read_u8 v0, v238 offset:16384
	ds_read_u8 v1, v238 offset:16385
	ds_read_u8 v2, v238 offset:16386
	ds_read_u8 v3, v238 offset:16387
	ds_read_u8 v4, v238 offset:16388
	ds_read_u8 v5, v238 offset:16389
	ds_read_u8 v6, v238 offset:16390
	s_waitcnt lgkmcnt(6)
	v_lshrrev_b32_e32 v7, 2, v0
	v_and_b32_e32 v0, 15, v0
	v_lshl_add_u32 v47, v0, 2, v31
	s_waitcnt lgkmcnt(5)
	v_lshrrev_b32_e32 v0, 2, v1
	v_and_b32_e32 v0, 60, v0
	v_add_u32_e32 v44, v31, v0
	v_and_b32_e32 v0, 15, v1
	v_lshl_add_u32 v45, v0, 2, v31
	s_waitcnt lgkmcnt(4)
	v_lshrrev_b32_e32 v0, 2, v2
	v_and_b32_e32 v0, 60, v0
	v_add_u32_e32 v42, v31, v0
	v_and_b32_e32 v0, 15, v2
	v_lshl_add_u32 v43, v0, 2, v31
	s_waitcnt lgkmcnt(3)
	v_lshrrev_b32_e32 v0, 2, v3
	v_and_b32_e32 v0, 60, v0
	v_add_u32_e32 v40, v31, v0
	v_and_b32_e32 v0, 15, v3
	v_lshl_add_u32 v41, v0, 2, v31
	s_waitcnt lgkmcnt(2)
	v_lshrrev_b32_e32 v0, 2, v4
	v_and_b32_e32 v0, 60, v0
	v_add_u32_e32 v38, v31, v0
	v_and_b32_e32 v0, 15, v4
	v_lshl_add_u32 v39, v0, 2, v31
	s_waitcnt lgkmcnt(1)
	v_lshrrev_b32_e32 v0, 2, v5
	v_and_b32_e32 v0, 60, v0
	v_and_b32_e32 v7, 60, v7
	v_add_u32_e32 v36, v31, v0
	v_and_b32_e32 v0, 15, v5
	v_add_u32_e32 v46, v31, v7
	v_lshl_add_u32 v37, v0, 2, v31
	s_waitcnt lgkmcnt(0)
	v_lshrrev_b32_e32 v0, 2, v6
	ds_read_b32 v48, v46 offset:2048
	ds_read_b32 v52, v47 offset:2112
	ds_read_b32 v51, v44 offset:2048
	ds_read_b32 v55, v45 offset:2112
	ds_read_b32 v50, v42 offset:2048
	ds_read_b32 v54, v43 offset:2112
	ds_read_b32 v49, v40 offset:2048
	ds_read_b32 v53, v41 offset:2112
	v_and_b32_e32 v0, 60, v0
	v_add_u32_e32 v34, v31, v0
	v_and_b32_e32 v0, 15, v6
	v_lshl_add_u32 v35, v0, 2, v31
	ds_read_b32 v59, v38 offset:2048
	ds_read_b32 v61, v39 offset:2112
	ds_read_b32 v57, v36 offset:2048
	ds_read_b32 v60, v37 offset:2112
	ds_read_b32 v56, v34 offset:2048
	ds_read_b32 v58, v35 offset:2112
	s_and_saveexec_b64 s[0:1], s[4:5]
	v_accvgpr_read_b32 v0, a76
	ds_write_b32 v0, a69 offset:1536
	s_or_b64 exec, exec, s[0:1]
	s_waitcnt lgkmcnt(12)
	v_add_f32_e32 v0, v48, v52
	v_and_or_b32 v52, v0, s33, v238
	s_waitcnt lgkmcnt(10)
	v_add_f32_e32 v0, v51, v55
	v_accvgpr_read_b32 v1, a68
	v_and_or_b32 v0, v0, s33, v1
	v_cndmask_b32_e64 v48, v0, v252, s[16:17]
	s_waitcnt lgkmcnt(8)
	v_add_f32_e32 v0, v50, v54
	v_and_or_b32 v0, v0, s33, v251
	v_cndmask_b32_e64 v51, v0, v252, s[16:17]
	s_waitcnt lgkmcnt(6)
	v_add_f32_e32 v0, v49, v53
	v_and_or_b32 v0, v0, s33, v181
	v_lshlrev_b64 v[200:201], 10, v[32:33]
	v_cndmask_b32_e64 v32, v0, v252, s[16:17]
	s_waitcnt lgkmcnt(4)
	v_add_f32_e32 v0, v59, v61
	v_and_or_b32 v0, v0, s33, v184
	v_cndmask_b32_e64 v33, v0, v252, s[16:17]
	s_waitcnt lgkmcnt(2)
	v_add_f32_e32 v0, v57, v60
	v_and_or_b32 v0, v0, s33, v245
	v_cndmask_b32_e64 v49, v0, v252, s[16:17]
	s_waitcnt lgkmcnt(0)
	v_add_f32_e32 v0, v56, v58
	v_and_or_b32 v0, v0, s33, v250
	v_cndmask_b32_e64 v50, v0, v252, s[16:17]
	v_max_f32_e32 v0, v52, v52
	v_max_f32_e32 v53, 0xff61b1e6, v0
	v_mov_b32_e32 v55, 0
	v_mov_b32_e32 v54, 0x7f61b1e6
	s_mov_b32 s0, 16

; #define DPP_F(v, ctrl) __int_as_float(__builtin_amdgcn_update_dpp(0, __float_as_int(v), (ctrl), 0xF, 0xF, true))
; __device__ __forceinline__ void phase5(const Params& p, char* smem, const bool store_x = true) {
;     ...
;       if (lane < 8) wcnt[lane] = 0;
;       float m = 3.0e38f, m1 = 0.f;
; #pragma unroll 1
;       for (int rd = 0; rd < 16; rd++) {
;         float loc = NINF;
; #pragma unroll
;         for (int sl = 0; sl < 7; sl++) loc = fmaxf(loc, key[sl] < m ? key[sl] : NINF);
;         loc = fmaxf(loc, DPP_F(loc, 0xB1)); loc = fmaxf(loc, DPP_F(loc, 0x4E)); loc = fmaxf(loc, DPP_F(loc, 0x141));
;         if (rd == 0) m1 = loc;
;         m = loc;
;       }
;       float ev[7]; float es = 0.f;
; #pragma unroll
;       for (int sl = 0; sl < 7; sl++) { ev[sl] = key[sl] >= m ? __expf(key[sl] - m1) : 0.f; es += ev[sl]; }
;       es += DPP_F(es, 0xB1); es += DPP_F(es, 0x4E); es += DPP_F(es, 0x141);
;       const float inv = 1.f / es;
; #pragma unroll
;       for (int sl = 0; sl < 7; sl++) {
;         if (key[sl] >= m) {
;           int pos = atomicAdd(&wcnt[hd], 1);
;           int ia = ti[ij[sl] >> 4], ib = ti[16 + (ij[sl] & 15)];
;           widx[hd * 16 + pos] = ia * 128 + ib;
;           wgate[hd * 16 + pos] = ev[sl] * inv;
;         }
;       }
.LBB0_1496:
	s_or_b64 exec, exec, s[18:19]
	v_mbcnt_lo_u32_b32 v0, -1, 0
	v_mbcnt_hi_u32_b32 v0, -1, v0
	v_lshl_add_u32 v1, v0, 3, v176
	ds_read_b64 v[2:3], v1
	ds_read_b64 v[4:5], v1 offset:512
	s_add_u32 s98, s80, 0x3bb5000
	s_addc_u32 s99, s81, 0
	v_lshl_add_u32 v6, v0, 3, v200
	v_lshrrev_b32_e32 v7, 8, v200
	v_add_u32_e32 v7, 0x1100000, v7
	v_mov_b32_e32 v20, 0
	s_waitcnt lgkmcnt(0)
	v_lshlrev_b32_e32 v16, 7, v2
	v_lshlrev_b32_e32 v17, 7, v3
	global_store_dwordx2 v6, v[16:17], s[98:99]
	global_store_dwordx2 v6, v[4:5], s[98:99] offset:512
	s_mov_b64 exec, 1
	global_store_dword v7, v20, s[98:99]
	s_mov_b64 exec, -1
	s_and_b64 vcc, exec, s[34:35]
	s_cbranch_vccnz .Lp5a_done
	s_branch .LBB0_1482
